# MFMA/LDS interleave: s5_b nt-loop and s5_d t-loop issue all LDS fragment reads up front with counted lgkmcnt; s5_d Toeplitz steps made branch-free with zero-masked fragments (bit-identical), on top of
# baseline (speedup 1.0000x reference)
; #define LAS __attribute__((address_space(3)))
; #define MFMA16(a, b, c) __builtin_amdgcn_mfma_f32_16x16x32_bf16((a), (b), (c), 0, 0, 0)
; DI void s5_b_lds(const Prm& p, LAS unsigned char* lds, int tid, int lane, int wave) {
;     ...
;             for (int nt = 0; nt < 8; ++nt) { f32x4 acc = {0.f, 0.f, 0.f, 0.f};
; #pragma unroll
;                 for (int ks = 0; ks < 8; ++ks) { const bf16x8 b = *(const LAS bf16x8*)(lds + (16 * nt + fr) * 528 + 64 * ks + 16 * fq); acc = MFMA16(uf[ks], b, acc); }
; #pragma unroll
;                 for (int j = 0; j < 4; ++j) { const int col = 16 * mt + 4 * fq + j; if (col < NCOL) p.XLOC[(size_t)col * 4096 + g * 128 + 16 * nt + fr] = acc[j]; } }
.LBB0_781:
	ds_read_b128 v[32:35], v36
	ds_read_b128 v[84:87], v36 offset:64
	ds_read_b128 v[220:223], v36 offset:128
	ds_read_b128 v[224:227], v36 offset:192
	ds_read_b128 v[228:231], v36 offset:256
	ds_read_b128 v[232:235], v36 offset:320
	ds_read_b128 v[236:239], v36 offset:384
	ds_read_b128 v[240:243], v36 offset:448
	s_waitcnt lgkmcnt(7)
	v_mfma_f32_16x16x32_bf16 v[32:35], v[0:3], v[32:35], 0
	s_waitcnt lgkmcnt(6)
	v_mfma_f32_16x16x32_bf16 v[32:35], v[4:7], v[84:87], v[32:35]
	s_waitcnt lgkmcnt(5)
	v_mfma_f32_16x16x32_bf16 v[32:35], v[8:11], v[220:223], v[32:35]
	s_waitcnt lgkmcnt(4)
	v_mfma_f32_16x16x32_bf16 v[32:35], v[12:15], v[224:227], v[32:35]
	s_waitcnt lgkmcnt(3)
	v_mfma_f32_16x16x32_bf16 v[32:35], v[16:19], v[228:231], v[32:35]
	s_waitcnt lgkmcnt(2)
	v_mfma_f32_16x16x32_bf16 v[32:35], v[20:23], v[232:235], v[32:35]
	s_waitcnt lgkmcnt(1)
	v_mfma_f32_16x16x32_bf16 v[32:35], v[24:27], v[236:239], v[32:35]
	s_waitcnt lgkmcnt(0)
	v_mfma_f32_16x16x32_bf16 v[32:35], v[28:31], v[240:243], v[32:35]
	s_and_saveexec_b64 s[14:15], s[0:1]
	s_cbranch_execz .LBB0_785
	v_lshl_add_u64 v[84:85], v[56:57], 0, s[12:13]
	s_nop 4
	global_store_dword v[84:85], v32, off
	s_or_b64 exec, exec, s[14:15]
	s_and_saveexec_b64 s[14:15], s[2:3]
	s_cbranch_execnz .LBB0_786

; #define LAS __attribute__((address_space(3)))
; #define MFMA16(a, b, c) __builtin_amdgcn_mfma_f32_16x16x32_bf16((a), (b), (c), 0, 0, 0)
; DI void s5_d_lds(const Prm& p, LAS unsigned char* lds, int tid, int lane, int wave) {
;     ...
;             for (int t = 0; t < 16; ++t) { f32x4 acc = {0.f, 0.f, 0.f, 0.f};
; #pragma unroll
;                 for (int ks = 0; ks < 8; ++ks) if (ks <= (t >> 1)) {
;                     const int tau = t - 2 * ks - hi;
;                     union { bf16x8 v; u32x4v u; } a; a.v = *(const LAS bf16x8*)(lds + (tau < 0 ? 0 : tau) * 768 + lb);
;                     if (tau < 0) a.u = (u32x4v){0u, 0u, 0u, 0u};
;                     acc = MFMA16(a.v, uf[ks], acc); }
.LBB0_1108:
	v_add_u32_e32 v90, s4, v79
	v_mov_b32_e32 v224, v90
	v_max_i32_e32 v192, 0, v224
	v_mad_u64_u32 v[192:193], s[2:3], v192, s11, v[54:55]
	ds_read_b128 v[192:195], v192
	v_add_u32_e32 v225, -2, v90
	v_max_i32_e32 v196, 0, v225
	v_mad_u64_u32 v[196:197], s[2:3], v196, s11, v[54:55]
	ds_read_b128 v[196:199], v196
	v_add_u32_e32 v226, -4, v90
	v_max_i32_e32 v200, 0, v226
	v_mad_u64_u32 v[200:201], s[2:3], v200, s11, v[54:55]
	ds_read_b128 v[200:203], v200
	v_add_u32_e32 v227, -6, v90
	v_max_i32_e32 v204, 0, v227
	v_mad_u64_u32 v[204:205], s[2:3], v204, s11, v[54:55]
	ds_read_b128 v[204:207], v204
	v_add_u32_e32 v228, -8, v90
	v_max_i32_e32 v208, 0, v228
	v_mad_u64_u32 v[208:209], s[2:3], v208, s11, v[54:55]
	ds_read_b128 v[208:211], v208
	v_add_u32_e32 v229, -10, v90
	v_max_i32_e32 v212, 0, v229
	v_mad_u64_u32 v[212:213], s[2:3], v212, s11, v[54:55]
	ds_read_b128 v[212:215], v212
	v_add_u32_e32 v230, -12, v90
	v_max_i32_e32 v216, 0, v230
	v_mad_u64_u32 v[216:217], s[2:3], v216, s11, v[54:55]
	ds_read_b128 v[216:219], v216
	v_add_u32_e32 v231, -14, v90
	v_max_i32_e32 v220, 0, v231
	v_mad_u64_u32 v[220:221], s[2:3], v220, s11, v[54:55]
	ds_read_b128 v[220:223], v220
	v_cmp_lt_i32_e64 s[54:55], -1, v224
	v_cmp_lt_i32_e64 s[56:57], -1, v225
	v_cmp_lt_i32_e64 s[58:59], -1, v226
	v_cmp_lt_i32_e64 s[60:61], -1, v227
	v_cmp_lt_i32_e64 s[62:63], -1, v228
	v_cmp_lt_i32_e64 s[64:65], -1, v229
	v_cmp_lt_i32_e64 s[66:67], -1, v230
	v_cmp_lt_i32_e64 s[68:69], -1, v231
	s_waitcnt lgkmcnt(7)
	v_cndmask_b32_e64 v195, 0, v195, s[54:55]
	v_cndmask_b32_e64 v194, 0, v194, s[54:55]
	v_cndmask_b32_e64 v193, 0, v193, s[54:55]
	v_cndmask_b32_e64 v192, 0, v192, s[54:55]
	s_waitcnt lgkmcnt(6)
	v_cndmask_b32_e64 v199, 0, v199, s[56:57]
	v_cndmask_b32_e64 v198, 0, v198, s[56:57]
	v_cndmask_b32_e64 v197, 0, v197, s[56:57]
	v_cndmask_b32_e64 v196, 0, v196, s[56:57]
	v_mfma_f32_16x16x32_bf16 v[48:51], v[192:195], v[0:3], 0
	s_waitcnt lgkmcnt(5)
	v_cndmask_b32_e64 v203, 0, v203, s[58:59]
	v_cndmask_b32_e64 v202, 0, v202, s[58:59]
	v_cndmask_b32_e64 v201, 0, v201, s[58:59]
	v_cndmask_b32_e64 v200, 0, v200, s[58:59]
	v_mfma_f32_16x16x32_bf16 v[48:51], v[196:199], v[4:7], v[48:51]
	s_waitcnt lgkmcnt(4)
	v_cndmask_b32_e64 v207, 0, v207, s[60:61]
	v_cndmask_b32_e64 v206, 0, v206, s[60:61]
	v_cndmask_b32_e64 v205, 0, v205, s[60:61]
	v_cndmask_b32_e64 v204, 0, v204, s[60:61]
	v_mfma_f32_16x16x32_bf16 v[48:51], v[200:203], v[8:11], v[48:51]
	s_waitcnt lgkmcnt(3)
	v_cndmask_b32_e64 v211, 0, v211, s[62:63]
	v_cndmask_b32_e64 v210, 0, v210, s[62:63]
	v_cndmask_b32_e64 v209, 0, v209, s[62:63]
	v_cndmask_b32_e64 v208, 0, v208, s[62:63]
	v_mfma_f32_16x16x32_bf16 v[48:51], v[204:207], v[12:15], v[48:51]
	s_waitcnt lgkmcnt(2)
	v_cndmask_b32_e64 v215, 0, v215, s[64:65]
	v_cndmask_b32_e64 v214, 0, v214, s[64:65]
	v_cndmask_b32_e64 v213, 0, v213, s[64:65]
	v_cndmask_b32_e64 v212, 0, v212, s[64:65]
	v_mfma_f32_16x16x32_bf16 v[48:51], v[208:211], v[16:19], v[48:51]
	s_waitcnt lgkmcnt(1)
	v_cndmask_b32_e64 v219, 0, v219, s[66:67]
	v_cndmask_b32_e64 v218, 0, v218, s[66:67]
	v_cndmask_b32_e64 v217, 0, v217, s[66:67]
	v_cndmask_b32_e64 v216, 0, v216, s[66:67]
	v_mfma_f32_16x16x32_bf16 v[48:51], v[212:215], v[20:23], v[48:51]
	s_waitcnt lgkmcnt(0)
	v_cndmask_b32_e64 v223, 0, v223, s[68:69]
	v_cndmask_b32_e64 v222, 0, v222, s[68:69]
	v_cndmask_b32_e64 v221, 0, v221, s[68:69]
	v_cndmask_b32_e64 v220, 0, v220, s[68:69]
	v_mfma_f32_16x16x32_bf16 v[48:51], v[216:219], v[24:27], v[48:51]
	s_nop 1
	v_mfma_f32_16x16x32_bf16 v[48:51], v[220:223], v[28:31], v[48:51]
; #define LAS __attribute__((address_space(3)))
; DI unsigned pk2(float lo, float hi) { unsigned r; asm volatile("v_cvt_pk_bf16_f32 %0, %1, %2" : "=v"(r) : "v"(lo), "v"(hi)); return r; }
; #define MFMA16(a, b, c) __builtin_amdgcn_mfma_f32_16x16x32_bf16((a), (b), (c), 0, 0, 0)
; DI f32x2v gelu_pk(f32x2v v) {
;     const f32x2v av = __builtin_elementwise_abs(v), d = av * 0.2316418882f + 1.0f;
;     f32x2v t; t.x = __builtin_amdgcn_rcpf(d.x); t.y = __builtin_amdgcn_rcpf(d.y);
;     f32x2v q = t * 0.5307027145f + (-0.7265760135f); q = q * t + 0.7107068705f; q = q * t + (-0.142248368f); q = q * t + 0.127414796f; q = q * t;
;     const f32x2v s = (v * v) * (-0.72134752044f);
;     f32x2v e; e.x = __builtin_amdgcn_exp2f(s.x); e.y = __builtin_amdgcn_exp2f(s.y);
;     const f32x2v m = v * (q * e), r = v - m;
;     f32x2v o; o.x = v.x < 0.f ? m.x : r.x; o.y = v.y < 0.f ? m.y : r.y; return o;
; }
; DI void s5_d_lds(const Prm& p, LAS unsigned char* lds, int tid, int lane, int wave) {
;     ...
; #pragma unroll
;                 for (int ks = 0; ks < 4; ++ks) { const bf16x8 a = *(const LAS bf16x8*)(lds + 12288 + (t * 16 + fr) * 272 + 64 * ks + 16 * fq); acc = MFMA16(a, xf[ks], acc); }
;                 const f32x2v y0 = gelu_pk((f32x2v){acc[0], acc[1]}), y1 = gelu_pk((f32x2v){acc[2], acc[3]});
;                 u32x2 o; o.x = pk2(y0.x, y0.y); o.y = pk2(y1.x, y1.y);
;                 if (ok) *(u32x2*)(p.YG + ((size_t)(16 * (16 * mt + fr) + t)) * 512 + 16 * g + 4 * fq) = o; }
.LBB0_1116:
	ds_read_b128 v[90:93], v89
	ds_read_b128 v[94:97], v89 offset:64
	s_waitcnt lgkmcnt(1)
	v_mfma_f32_16x16x32_bf16 v[48:51], v[90:93], v[32:35], v[48:51]
	ds_read_b128 v[90:93], v89 offset:128
	s_waitcnt lgkmcnt(1)
	v_mfma_f32_16x16x32_bf16 v[48:51], v[94:97], v[36:39], v[48:51]
	ds_read_b128 v[94:97], v89 offset:192
	s_waitcnt lgkmcnt(1)
	v_mfma_f32_16x16x32_bf16 v[48:51], v[90:93], v[40:43], v[48:51]
	v_mov_b64_e32 v[90:91], s[10:11]
	s_waitcnt lgkmcnt(0)
	v_mfma_f32_16x16x32_bf16 v[48:51], v[94:97], v[44:47], v[48:51]
	s_nop 7
	v_and_b32_e32 v93, 0x7fffffff, v49
	v_and_b32_e32 v92, 0x7fffffff, v48
	v_pk_fma_f32 v[92:93], v[92:93], s[6:7], 1.0 op_sel_hi:[1,0,0]
	v_pk_mul_f32 v[96:97], v[48:49], v[48:49]
	v_rcp_f32_e32 v92, v92
	v_rcp_f32_e32 v93, v93
	v_and_b32_e32 v99, 0x7fffffff, v51
	v_and_b32_e32 v98, 0x7fffffff, v50
	v_pk_mul_f32 v[96:97], v[96:97], s[18:19] op_sel_hi:[1,0]
	v_pk_fma_f32 v[100:101], v[92:93], s[8:9], v[90:91] op_sel_hi:[1,0,0]
	v_pk_fma_f32 v[98:99], v[98:99], s[6:7], 1.0 op_sel_hi:[1,0,0]
	v_exp_f32_e32 v96, v96
	v_exp_f32_e32 v97, v97
	v_pk_fma_f32 v[100:101], v[92:93], v[100:101], s[12:13] op_sel_hi:[1,1,0]
	v_rcp_f32_e32 v98, v98
	v_rcp_f32_e32 v99, v99
	v_pk_fma_f32 v[100:101], v[92:93], v[100:101], s[14:15] op_sel_hi:[1,1,0]
	v_pk_mul_f32 v[94:95], v[50:51], v[50:51]
	v_pk_fma_f32 v[100:101], v[92:93], v[100:101], s[16:17] op_sel_hi:[1,1,0]
	v_pk_mul_f32 v[94:95], v[94:95], s[18:19] op_sel_hi:[1,0]
	v_pk_mul_f32 v[92:93], v[92:93], v[100:101]
	v_pk_fma_f32 v[90:91], v[98:99], s[8:9], v[90:91] op_sel_hi:[1,0,0]
	v_pk_mul_f32 v[92:93], v[96:97], v[92:93]
	v_cmp_gt_f32_e64 s[2:3], 0, v48
	v_pk_mul_f32 v[96:97], v[48:49], v[92:93]
	v_pk_fma_f32 v[92:93], v[48:49], v[92:93], v[48:49] neg_lo:[1,0,0] neg_hi:[1,0,0]
	v_pk_fma_f32 v[90:91], v[98:99], v[90:91], s[12:13] op_sel_hi:[1,1,0]
	v_cndmask_b32_e64 v92, v92, v96, s[2:3]
	v_cmp_gt_f32_e64 s[2:3], 0, v49
	v_exp_f32_e32 v48, v94
	v_exp_f32_e32 v49, v95
	v_pk_fma_f32 v[90:91], v[98:99], v[90:91], s[14:15] op_sel_hi:[1,1,0]
	v_cndmask_b32_e64 v93, v93, v97, s[2:3]
	v_pk_fma_f32 v[90:91], v[98:99], v[90:91], s[16:17] op_sel_hi:[1,1,0]
	v_cmp_gt_f32_e64 s[2:3], 0, v50
	v_pk_mul_f32 v[90:91], v[98:99], v[90:91]
	s_nop 0
	v_pk_mul_f32 v[48:49], v[48:49], v[90:91]
	s_nop 0
	v_pk_mul_f32 v[90:91], v[50:51], v[48:49]
	v_pk_fma_f32 v[48:49], v[50:51], v[48:49], v[50:51] neg_lo:[1,0,0] neg_hi:[1,0,0]
	s_nop 0
	v_cndmask_b32_e64 v50, v48, v90, s[2:3]
	v_cmp_gt_f32_e64 s[2:3], 0, v51
	v_cvt_pk_bf16_f32 v48, v92, v93
	s_nop 1
	v_cndmask_b32_e64 v49, v49, v91, s[2:3]
	v_cvt_pk_bf16_f32 v49, v50, v49
	s_and_saveexec_b64 s[2:3], s[0:1]
	s_cbranch_execz .LBB0_1107
	v_add_u32_e32 v50, s4, v52
	v_ashrrev_i32_e32 v51, 31, v50
	v_lshlrev_b64 v[50:51], 10, v[50:51]
	v_lshl_add_u64 v[50:51], v[70:71], 0, v[50:51]
	global_store_dwordx2 v[50:51], v[48:49], off
	s_branch .LBB0_1107
.LBB0_1124:
	s_waitcnt vmcnt(0)
	s_barrier
	s_mov_b64 s[0:1], exec
	v_readlane_b32 s2, v254, 10
	v_readlane_b32 s3, v254, 11
	s_and_b64 s[2:3], s[0:1], s[2:3]
	s_mov_b64 exec, s[2:3]
	s_cbranch_execz .LBB0_1176
	s_add_i32 s2, 0, 0x20000
	s_waitcnt vmcnt(0)
	v_mov_b32_e32 v0, s2
	s_waitcnt vmcnt(0) expcnt(0) lgkmcnt(0)
	ds_read_b32 v2, v0
	s_add_i32 s2, 0, 0x20004
	v_mov_b32_e32 v0, s2
	ds_read_b32 v0, v0
	s_waitcnt lgkmcnt(1)
	v_cmp_ne_u32_e32 vcc, 0, v2
	s_cbranch_vccnz .LBB0_1140
	v_readlane_b32 s2, v254, 8
	s_mul_i32 s16, s89, s2
	s_add_u32 s2, s94, 0x1000
	s_addc_u32 s3, s95, 0
	s_add_u32 s4, s94, 0x1100
	s_addc_u32 s5, s95, 0
	s_add_u32 s6, s94, 0x1200
	s_addc_u32 s7, s95, 0
	s_add_u32 s8, s94, 0x1300
	s_mul_i32 s16, s16, s88
	s_addc_u32 s9, s95, 0
	s_mov_b32 s17, 1
	v_mov_b32_e32 v16, 0
	s_branch .LBB0_1128
